# MLA loop: V reads first, K fragments 7 deep using scratch quads and not-yet-written score registers, restaging behind the first three MFMA steps; on conflict-free K layouts and the diff-loop changes
# speedup vs baseline: 1.0154x; 1.0118x over previous
.LBB0_190:
	s_bitcmp1_b32 s1, 0
	s_cselect_b32 s0, 0x7000, 0
	v_add_u32_e32 v100, s0, v174
	v_add3_u32 v185, s0, v192, v159
	v_add3_u32 v100, v100, v175, v176
	v_add_u32_e32 v184, v100, v177
	v_add_u32_e32 v183, v100, v178
	v_add_u32_e32 v182, v100, v179
	v_add_u32_e32 v181, v100, v180
	ds_read_b64_tr_b16 v[112:113], v184 offset:20480
	ds_read_b64_tr_b16 v[114:115], v184 offset:20992
	ds_read_b64_tr_b16 v[108:109], v183 offset:20480
	ds_read_b64_tr_b16 v[110:111], v183 offset:20992
	ds_read_b64_tr_b16 v[104:105], v182 offset:20480
	ds_read_b64_tr_b16 v[106:107], v182 offset:20992
	ds_read_b64_tr_b16 v[100:101], v181 offset:20480
	ds_read_b64_tr_b16 v[102:103], v181 offset:20992
	ds_read_b128 v[186:189], v185
	ds_read_b128 v[194:197], v185 offset:64
	ds_read_b128 v[202:205], v185 offset:128
	ds_read_b128 v[144:147], v185 offset:1280
	ds_read_b128 v[128:131], v185 offset:1344
	ds_read_b128 v[140:143], v185 offset:1408
	ds_read_b128 v[124:127], v185 offset:10240
	s_waitcnt lgkmcnt(6)
	v_mfma_f32_16x16x32_bf16 v[136:139], v[186:189], v[12:15], v[36:39]
	v_mfma_f32_16x16x32_bf16 v[120:123], v[186:189], v[20:23], v[48:51]
	ds_read_b128 v[186:189], v185 offset:10304
	s_waitcnt lgkmcnt(6)
	v_mfma_f32_16x16x32_bf16 v[136:139], v[194:197], v[16:19], v[136:139]
	v_mfma_f32_16x16x32_bf16 v[120:123], v[194:197], v[24:27], v[120:123]
	ds_read_b128 v[194:197], v185 offset:10368
	s_waitcnt lgkmcnt(6)
	v_mfma_f32_16x16x32_bf16 v[136:139], v[202:205], v[0:3], v[136:139]
	v_mfma_f32_16x16x32_bf16 v[120:123], v[202:205], v[4:7], v[120:123]
	ds_read_b128 v[202:205], v185 offset:11520
	s_andn2_b32 s0, 1, s1
	s_mulk_i32 s0, 0x7000
	s_add_i32 s10, s1, 1
	v_add3_u32 v132, s0, v151, v155
	v_add3_u32 v133, s0, v157, v170
	v_add_u32_e32 v134, s0, v171
	s_waitcnt vmcnt(2)
	ds_write_b128 v132, v[8:11]
	v_add3_u32 v134, v134, v173, v172
	s_add_i32 s0, s1, 3
	s_min_u32 s0, s0, s83
	s_waitcnt vmcnt(0)
	ds_write_b128 v133, v[28:31]
	s_lshl_b32 s0, s0, 6
	ds_write_b128 v134, v[32:35] offset:20480
	v_add_u32_e32 v8, s0, v154
	v_add_u32_e32 v28, s0, v156
	s_add_i32 s0, s1, 2
	v_ashrrev_i32_e32 v9, 31, v8
	v_ashrrev_i32_e32 v29, 31, v28
	s_min_u32 s0, s0, s83
	v_lshlrev_b64 v[10:11], 11, v[8:9]
	v_lshlrev_b64 v[8:9], 6, v[8:9]
	v_lshlrev_b64 v[30:31], 11, v[28:29]
	v_lshlrev_b64 v[28:29], 6, v[28:29]
	v_lshl_add_u32 v32, s0, 6, v158
	v_lshl_add_u64 v[8:9], v[162:163], 0, v[8:9]
	v_lshl_add_u64 v[28:29], v[166:167], 0, v[28:29]
	v_ashrrev_i32_e32 v33, 31, v32
	v_lshl_add_u64 v[10:11], v[164:165], 0, v[10:11]
	v_lshl_add_u64 v[8:9], v[8:9], 0, s[58:59]
	v_lshl_add_u64 v[30:31], v[168:169], 0, v[30:31]
	v_lshl_add_u64 v[28:29], v[28:29], 0, s[58:59]
	v_lshlrev_b64 v[32:33], 11, v[32:33]
	v_cndmask_b32_e64 v9, v9, v11, s[6:7]
	v_cndmask_b32_e64 v8, v8, v10, s[6:7]
	v_cndmask_b32_e64 v29, v29, v31, s[8:9]
	v_cndmask_b32_e64 v28, v28, v30, s[8:9]
	v_lshl_add_u64 v[32:33], v[160:161], 0, v[32:33]
	global_load_dwordx4 v[8:11], v[8:9], off
	global_load_dwordx4 v[28:31], v[28:29], off
	global_load_dwordx4 v[32:35], v[32:33], off offset:128
	s_waitcnt lgkmcnt(9)
	v_mfma_f32_16x16x32_bf16 v[132:135], v[144:147], v[12:15], v[36:39]
	v_mfma_f32_16x16x32_bf16 v[116:119], v[144:147], v[20:23], v[48:51]
	s_waitcnt lgkmcnt(8)
	v_mfma_f32_16x16x32_bf16 v[132:135], v[128:131], v[16:19], v[132:135]
	v_mfma_f32_16x16x32_bf16 v[116:119], v[128:131], v[24:27], v[116:119]
	s_waitcnt lgkmcnt(7)
	v_mfma_f32_16x16x32_bf16 v[132:135], v[140:143], v[0:3], v[132:135]
	v_mfma_f32_16x16x32_bf16 v[116:119], v[140:143], v[4:7], v[116:119]
	s_waitcnt lgkmcnt(6)
	v_mfma_f32_16x16x32_bf16 v[140:143], v[124:127], v[12:15], v[36:39]
	v_mfma_f32_16x16x32_bf16 v[124:127], v[124:127], v[20:23], v[48:51]
	s_waitcnt lgkmcnt(5)
	v_mfma_f32_16x16x32_bf16 v[140:143], v[186:189], v[16:19], v[140:143]
	v_mfma_f32_16x16x32_bf16 v[124:127], v[186:189], v[24:27], v[124:127]
	ds_read_b128 v[186:189], v185 offset:11584
	s_waitcnt lgkmcnt(5)
	v_mfma_f32_16x16x32_bf16 v[140:143], v[194:197], v[0:3], v[140:143]
	v_mfma_f32_16x16x32_bf16 v[124:127], v[194:197], v[4:7], v[124:127]
	ds_read_b128 v[194:197], v185 offset:11648
	s_waitcnt lgkmcnt(5)
	v_mfma_f32_16x16x32_bf16 v[144:147], v[202:205], v[12:15], v[36:39]
	v_mfma_f32_16x16x32_bf16 v[128:131], v[202:205], v[20:23], v[48:51]
	s_waitcnt lgkmcnt(1)
	v_mfma_f32_16x16x32_bf16 v[144:147], v[186:189], v[16:19], v[144:147]
	v_mfma_f32_16x16x32_bf16 v[128:131], v[186:189], v[24:27], v[128:131]
	s_waitcnt lgkmcnt(0)
	v_mfma_f32_16x16x32_bf16 v[144:147], v[194:197], v[0:3], v[144:147]
	v_mfma_f32_16x16x32_bf16 v[128:131], v[194:197], v[4:7], v[128:131]
	s_cmp_ge_u32 s10, s82
	s_cbranch_scc1 .LBB0_196
	s_cmp_lg_u32 s1, 0
	s_cselect_b64 s[0:1], -1, 0
	s_and_b32 s11, s10, 3
	s_cmp_lg_u32 s11, 0
	s_cselect_b64 s[14:15], -1, 0
	s_and_b64 s[0:1], s[0:1], s[14:15]
	s_and_b64 vcc, exec, s[0:1]
	s_cbranch_vccnz .LBB0_196
	v_max_f32_e32 v185, v137, v137
	v_max_f32_e32 v186, v136, v136
	v_max_f32_e32 v185, v186, v185
	v_max3_f32 v185, v185, v138, v139
	v_max3_f32 v185, v185, v132, v133
	v_max3_f32 v185, v185, v134, v135
	v_max3_f32 v185, v185, v140, v141
	v_max3_f32 v185, v185, v142, v143
	v_max3_f32 v185, v185, v144, v145
	v_max3_f32 v185, v185, v146, v147
	v_mov_b32_e32 v186, v185
	s_nop 1
	v_permlane16_swap_b32_e32 v185, v186
	v_max_f32_e32 v186, v186, v186
	v_max_f32_e32 v185, v185, v185
	v_max_f32_e32 v185, v185, v186
	v_mov_b32_e32 v186, v185
	s_nop 1
	v_permlane32_swap_b32_e32 v185, v186
	v_max_f32_e32 v186, v186, v186
	v_max_f32_e32 v185, v185, v185
	v_max_f32_e32 v185, v185, v186
	v_cmp_lt_f32_e32 vcc, s44, v185
	s_cbranch_vccz .LBB0_194
	s_nop 0
	v_cndmask_b32_e32 v185, 0, v185, vcc
	v_exp_f32_e64 v186, -v185
	v_lshlrev_b32_e32 v188, 16, v56
	v_and_b32_e32 v189, 0xffff0000, v56
	v_sub_f32_e32 v139, v139, v185
	v_pk_mul_f32 v[188:189], v[186:187], v[188:189] op_sel_hi:[0,1]
	v_cvt_pk_bf16_f32 v56, v188, v189
	v_lshlrev_b32_e32 v188, 16, v57
	v_and_b32_e32 v189, 0xffff0000, v57
	v_pk_mul_f32 v[188:189], v[186:187], v[188:189] op_sel_hi:[0,1]
	v_cvt_pk_bf16_f32 v57, v188, v189
	v_lshlrev_b32_e32 v188, 16, v58
	v_and_b32_e32 v189, 0xffff0000, v58
	v_pk_mul_f32 v[188:189], v[186:187], v[188:189] op_sel_hi:[0,1]
	v_cvt_pk_bf16_f32 v58, v188, v189
	v_lshlrev_b32_e32 v188, 16, v59
	v_and_b32_e32 v189, 0xffff0000, v59
	v_pk_mul_f32 v[188:189], v[186:187], v[188:189] op_sel_hi:[0,1]
	v_cvt_pk_bf16_f32 v59, v188, v189
	v_lshlrev_b32_e32 v188, 16, v52
	v_and_b32_e32 v189, 0xffff0000, v52
	v_pk_mul_f32 v[188:189], v[186:187], v[188:189] op_sel_hi:[0,1]
	v_cvt_pk_bf16_f32 v52, v188, v189
	v_lshlrev_b32_e32 v188, 16, v53
	v_and_b32_e32 v189, 0xffff0000, v53
	v_pk_mul_f32 v[188:189], v[186:187], v[188:189] op_sel_hi:[0,1]
	v_cvt_pk_bf16_f32 v53, v188, v189
	v_lshlrev_b32_e32 v188, 16, v54
	v_and_b32_e32 v189, 0xffff0000, v54
	v_pk_mul_f32 v[188:189], v[186:187], v[188:189] op_sel_hi:[0,1]
	v_cvt_pk_bf16_f32 v54, v188, v189
	v_lshlrev_b32_e32 v188, 16, v55
	v_and_b32_e32 v189, 0xffff0000, v55
	v_pk_mul_f32 v[78:79], v[78:79], v[186:187] op_sel_hi:[1,0]
	v_pk_mul_f32 v[76:77], v[76:77], v[186:187] op_sel_hi:[1,0]
	v_pk_mul_f32 v[98:99], v[98:99], v[186:187] op_sel_hi:[1,0]
	v_pk_mul_f32 v[96:97], v[96:97], v[186:187] op_sel_hi:[1,0]
	v_pk_mul_f32 v[94:95], v[94:95], v[186:187] op_sel_hi:[1,0]
	v_pk_mul_f32 v[92:93], v[92:93], v[186:187] op_sel_hi:[1,0]
	v_pk_mul_f32 v[86:87], v[86:87], v[186:187] op_sel_hi:[1,0]
	v_pk_mul_f32 v[84:85], v[84:85], v[186:187] op_sel_hi:[1,0]
	v_pk_mul_f32 v[42:43], v[42:43], v[186:187] op_sel_hi:[1,0]
	v_pk_mul_f32 v[40:41], v[40:41], v[186:187] op_sel_hi:[1,0]
	v_pk_mul_f32 v[186:187], v[186:187], v[188:189] op_sel_hi:[0,1]
	v_sub_f32_e32 v138, v138, v185
	v_sub_f32_e32 v137, v137, v185
	v_sub_f32_e32 v136, v136, v185
	v_sub_f32_e32 v135, v135, v185
	v_sub_f32_e32 v134, v134, v185
	v_sub_f32_e32 v133, v133, v185
	v_sub_f32_e32 v132, v132, v185
	v_sub_f32_e32 v143, v143, v185
	v_sub_f32_e32 v142, v142, v185
	v_sub_f32_e32 v141, v141, v185
	v_sub_f32_e32 v140, v140, v185
	v_sub_f32_e32 v147, v147, v185
	v_sub_f32_e32 v146, v146, v185
	v_sub_f32_e32 v145, v145, v185
	v_sub_f32_e32 v144, v144, v185
	v_cvt_pk_bf16_f32 v55, v186, v187
	v_sub_f32_e32 v39, v39, v185
	v_sub_f32_e32 v38, v38, v185
	v_sub_f32_e32 v37, v37, v185
	v_sub_f32_e32 v36, v36, v185
